# init pass writes the RMSNorm row-sum partials for the input rows (dot2c + 16-lane DPP), so the first FFN GEMM also drops its Gram MFMAs; init loop keeps 8 row loads in flight
# baseline (speedup 1.0000x reference)
; DI int opaque_tid() { int t = threadIdx.x; asm volatile("" : "+v"(t)); return t; }
; DI void init_h(const Params& p) {
;   float* h = (float*)(p.ws + OFF_H);
;   u16* hb = (u16*)(p.ws + OFF_HB);
;   const size_t n4 = (size_t)M * D / 4;
;   for (size_t i = (size_t)blockIdx.x * NT + opaque_tid(); i < n4; i += (size_t)gridDim.x * NT) {
;     const size_t e = i * 4;
;     const int row = (int)(e / D), col = (int)(e % D);
;     const int b = row / T, t = row % T;
;     f32x4 v = t < 16 ? *(const f32x4*)(p.meta + (size_t)t * D + col) : *(const f32x4*)(p.x + ((size_t)b * 2048 + (t - 16)) * D + col);
;     *(f32x4*)(h + e) = v;
;     *(u32x2*)(hb + e) = MK2(pack2(v[0], v[1]), pack2(v[2], v[3]));
;   }
.LBB0_5:
	s_or_b64 exec, exec, s[2:3]
	s_load_dwordx16 s[36:51], s[0:1], 0x0
	v_mov_b32_e32 v8, v210
	s_waitcnt lgkmcnt(0)
	v_writelane_b32 v252, s36, 6
	s_nop 1
	v_writelane_b32 v252, s37, 7
	v_writelane_b32 v252, s38, 8
	v_writelane_b32 v252, s39, 9
	v_writelane_b32 v252, s40, 10
	v_writelane_b32 v252, s41, 11
	v_writelane_b32 v252, s42, 12
	v_writelane_b32 v252, s43, 13
	v_writelane_b32 v252, s44, 14
	v_writelane_b32 v252, s45, 15
	v_writelane_b32 v252, s46, 16
	v_writelane_b32 v252, s47, 17
	v_writelane_b32 v252, s48, 18
	v_writelane_b32 v252, s49, 19
	v_writelane_b32 v252, s50, 20
	v_writelane_b32 v252, s51, 21
	s_cmpk_lg_i32 s26, 0x100
	s_cbranch_scc1 .Linit_generic
	s_load_dwordx4 s[36:39], s[0:1], 0x0
	v_readlane_b32 s14, v252, 0
	s_mov_b64 s[2:3], exec
	s_nop 0
	s_lshl_b32 s6, s14, 9
	v_add_u32_e32 v2, s6, v210
	v_mov_b32_e32 v3, 0
	v_mov_b32_e32 v21, 0
	v_lshl_add_u64 v[4:5], v[2:3], 4, s[24:25]
	v_lshl_add_u64 v[6:7], v[2:3], 3, s[24:25]
	s_mov_b64 s[10:11], 0x4080000
	v_lshl_add_u64 v[6:7], v[6:7], 0, s[10:11]
	s_add_u32 s16, s24, 0x15fe9000
	s_addc_u32 s17, s25, 0
	s_mov_b64 s[8:9], 0x200000
	s_mov_b64 s[10:11], 0x100000
	s_waitcnt lgkmcnt(0)
	v_mov_b32_e32 v16, s38
	v_mov_b32_e32 v17, s39
	v_mov_b32_e32 v18, s36
	v_mov_b32_e32 v19, s37
	s_mov_b32 s12, 0
.Linit_loop:
	v_mov_b32_e32 v22, v2
	v_lshrrev_b32_e32 v23, 8, v22
	v_and_b32_e32 v22, 0xff, v22
	v_mul_u32_u24_e32 v24, 0x3f81, v23
	v_lshrrev_b32_e32 v24, 25, v24
	v_mul_u32_u24_e32 v25, 0x810, v24
	v_sub_u32_e32 v25, v23, v25
	v_cmp_lt_u32_e32 vcc, 15, v25
	v_lshl_add_u32 v26, v24, 11, v25
	v_add_u32_e32 v26, -16, v26
	v_lshlrev_b32_e32 v22, 4, v22
	v_cndmask_b32_e32 v26, v25, v26, vcc
	v_cndmask_b32_e32 v28, v16, v18, vcc
	v_cndmask_b32_e32 v29, v17, v19, vcc
	v_lshl_or_b32 v20, v26, 12, v22
	v_lshl_add_u64 v[30:31], v[20:21], 0, v[28:29]
	global_load_dwordx4 v[48:51], v[30:31], off
	v_add_u32_e32 v22, 0x20000, v2
	v_lshrrev_b32_e32 v23, 8, v22
	v_and_b32_e32 v22, 0xff, v22
	v_mul_u32_u24_e32 v24, 0x3f81, v23
	v_lshrrev_b32_e32 v24, 25, v24
	v_mul_u32_u24_e32 v25, 0x810, v24
	v_sub_u32_e32 v25, v23, v25
	v_cmp_lt_u32_e32 vcc, 15, v25
	v_lshl_add_u32 v26, v24, 11, v25
	v_add_u32_e32 v26, -16, v26
	v_lshlrev_b32_e32 v22, 4, v22
	v_cndmask_b32_e32 v26, v25, v26, vcc
	v_cndmask_b32_e32 v28, v16, v18, vcc
	v_cndmask_b32_e32 v29, v17, v19, vcc
	v_lshl_or_b32 v20, v26, 12, v22
	v_lshl_add_u64 v[32:33], v[20:21], 0, v[28:29]
	global_load_dwordx4 v[52:55], v[32:33], off
	v_add_u32_e32 v22, 0x40000, v2
	v_lshrrev_b32_e32 v23, 8, v22
	v_and_b32_e32 v22, 0xff, v22
	v_mul_u32_u24_e32 v24, 0x3f81, v23
	v_lshrrev_b32_e32 v24, 25, v24
	v_mul_u32_u24_e32 v25, 0x810, v24
	v_sub_u32_e32 v25, v23, v25
	v_cmp_lt_u32_e32 vcc, 15, v25
	v_lshl_add_u32 v26, v24, 11, v25
	v_add_u32_e32 v26, -16, v26
	v_lshlrev_b32_e32 v22, 4, v22
	v_cndmask_b32_e32 v26, v25, v26, vcc
	v_cndmask_b32_e32 v28, v16, v18, vcc
	v_cndmask_b32_e32 v29, v17, v19, vcc
	v_lshl_or_b32 v20, v26, 12, v22
	v_lshl_add_u64 v[34:35], v[20:21], 0, v[28:29]
	global_load_dwordx4 v[56:59], v[34:35], off
	v_add_u32_e32 v22, 0x60000, v2
	v_lshrrev_b32_e32 v23, 8, v22
	v_and_b32_e32 v22, 0xff, v22
	v_mul_u32_u24_e32 v24, 0x3f81, v23
	v_lshrrev_b32_e32 v24, 25, v24
	v_mul_u32_u24_e32 v25, 0x810, v24
	v_sub_u32_e32 v25, v23, v25
	v_cmp_lt_u32_e32 vcc, 15, v25
	v_lshl_add_u32 v26, v24, 11, v25
	v_add_u32_e32 v26, -16, v26
	v_lshlrev_b32_e32 v22, 4, v22
	v_cndmask_b32_e32 v26, v25, v26, vcc
	v_cndmask_b32_e32 v28, v16, v18, vcc
	v_cndmask_b32_e32 v29, v17, v19, vcc
	v_lshl_or_b32 v20, v26, 12, v22
	v_lshl_add_u64 v[36:37], v[20:21], 0, v[28:29]
	global_load_dwordx4 v[60:63], v[36:37], off
	v_add_u32_e32 v22, 0x80000, v2
	v_lshrrev_b32_e32 v23, 8, v22
	v_and_b32_e32 v22, 0xff, v22
	v_mul_u32_u24_e32 v24, 0x3f81, v23
	v_lshrrev_b32_e32 v24, 25, v24
	v_mul_u32_u24_e32 v25, 0x810, v24
	v_sub_u32_e32 v25, v23, v25
	v_cmp_lt_u32_e32 vcc, 15, v25
	v_lshl_add_u32 v26, v24, 11, v25
	v_add_u32_e32 v26, -16, v26
	v_lshlrev_b32_e32 v22, 4, v22
	v_cndmask_b32_e32 v26, v25, v26, vcc
	v_cndmask_b32_e32 v28, v16, v18, vcc
	v_cndmask_b32_e32 v29, v17, v19, vcc
	v_lshl_or_b32 v20, v26, 12, v22
	v_lshl_add_u64 v[38:39], v[20:21], 0, v[28:29]
	global_load_dwordx4 v[64:67], v[38:39], off
	v_add_u32_e32 v22, 0xa0000, v2
	v_lshrrev_b32_e32 v23, 8, v22
	v_and_b32_e32 v22, 0xff, v22
	v_mul_u32_u24_e32 v24, 0x3f81, v23
	v_lshrrev_b32_e32 v24, 25, v24
	v_mul_u32_u24_e32 v25, 0x810, v24
	v_sub_u32_e32 v25, v23, v25
	v_cmp_lt_u32_e32 vcc, 15, v25
	v_lshl_add_u32 v26, v24, 11, v25
	v_add_u32_e32 v26, -16, v26
	v_lshlrev_b32_e32 v22, 4, v22
	v_cndmask_b32_e32 v26, v25, v26, vcc
	v_cndmask_b32_e32 v28, v16, v18, vcc
	v_cndmask_b32_e32 v29, v17, v19, vcc
	v_lshl_or_b32 v20, v26, 12, v22
	v_lshl_add_u64 v[40:41], v[20:21], 0, v[28:29]
	global_load_dwordx4 v[68:71], v[40:41], off
	v_add_u32_e32 v22, 0xc0000, v2
	v_lshrrev_b32_e32 v23, 8, v22
	v_and_b32_e32 v22, 0xff, v22
	v_mul_u32_u24_e32 v24, 0x3f81, v23
	v_lshrrev_b32_e32 v24, 25, v24
	v_mul_u32_u24_e32 v25, 0x810, v24
	v_sub_u32_e32 v25, v23, v25
	v_cmp_lt_u32_e32 vcc, 15, v25
	v_lshl_add_u32 v26, v24, 11, v25
	v_add_u32_e32 v26, -16, v26
	v_lshlrev_b32_e32 v22, 4, v22
	v_cndmask_b32_e32 v26, v25, v26, vcc
	v_cndmask_b32_e32 v28, v16, v18, vcc
	v_cndmask_b32_e32 v29, v17, v19, vcc
	v_lshl_or_b32 v20, v26, 12, v22
	v_lshl_add_u64 v[42:43], v[20:21], 0, v[28:29]
	global_load_dwordx4 v[72:75], v[42:43], off
	v_add_u32_e32 v22, 0xe0000, v2
	v_lshrrev_b32_e32 v23, 8, v22
	v_and_b32_e32 v22, 0xff, v22
	v_mul_u32_u24_e32 v24, 0x3f81, v23
	v_lshrrev_b32_e32 v24, 25, v24
	v_mul_u32_u24_e32 v25, 0x810, v24
	v_sub_u32_e32 v25, v23, v25
	v_cmp_lt_u32_e32 vcc, 15, v25
	v_lshl_add_u32 v26, v24, 11, v25
	v_add_u32_e32 v26, -16, v26
	v_lshlrev_b32_e32 v22, 4, v22
	v_cndmask_b32_e32 v26, v25, v26, vcc
	v_cndmask_b32_e32 v28, v16, v18, vcc
	v_cndmask_b32_e32 v29, v17, v19, vcc
	v_lshl_or_b32 v20, v26, 12, v22
	v_lshl_add_u64 v[44:45], v[20:21], 0, v[28:29]
	global_load_dwordx4 v[76:79], v[44:45], off
	s_waitcnt vmcnt(7)
; DI int opaque_tid() { int t = threadIdx.x; asm volatile("" : "+v"(t)); return t; }
; DI void init_h(const Params& p) {
;     ...
;   for (size_t i = (size_t)blockIdx.x * NT + opaque_tid(); i < n4; i += (size_t)gridDim.x * NT) {
;     const size_t e = i * 4;
;     const int row = (int)(e / D), col = (int)(e % D);
;     const int b = row / T, t = row % T;
;     f32x4 v = t < 16 ? *(const f32x4*)(p.meta + (size_t)t * D + col) : *(const f32x4*)(p.x + ((size_t)b * 2048 + (t - 16)) * D + col);
;     *(f32x4*)(h + e) = v;
;     *(u32x2*)(hb + e) = MK2(pack2(v[0], v[1]), pack2(v[2], v[3]));
;   }
	global_store_dwordx4 v[4:5], v[48:51], off
	v_cvt_pk_bf16_f32 v80, v48, v49
	v_cvt_pk_bf16_f32 v81, v50, v51
	v_lshl_add_u64 v[4:5], v[4:5], 0, s[8:9]
	global_store_dwordx2 v[6:7], v[80:81], off
	v_lshl_add_u64 v[6:7], v[6:7], 0, s[10:11]
	v_mov_b32_e32 v84, 0
	v_dot2c_f32_bf16_e32 v84, v80, v80
	v_dot2c_f32_bf16_e32 v84, v81, v81
	v_mov_b32_e32 v85, v2
	v_lshrrev_b32_e32 v85, 4, v85
	v_lshlrev_b32_e32 v85, 2, v85
	s_nop 1
	v_add_f32_dpp v84, v84, v84 quad_perm:[1,0,3,2] row_mask:0xf bank_mask:0xf
	s_nop 1
	v_add_f32_dpp v84, v84, v84 quad_perm:[2,3,0,1] row_mask:0xf bank_mask:0xf
	s_nop 1
	v_add_f32_dpp v84, v84, v84 row_half_mirror row_mask:0xf bank_mask:0xf
	s_nop 1
	v_add_f32_dpp v84, v84, v84 row_mirror row_mask:0xf bank_mask:0xf
	s_nop 1
	global_store_dword v85, v84, s[16:17]
	s_waitcnt vmcnt(9)
	global_store_dwordx4 v[4:5], v[52:55], off
	v_cvt_pk_bf16_f32 v82, v52, v53
	v_cvt_pk_bf16_f32 v83, v54, v55
	v_lshl_add_u64 v[4:5], v[4:5], 0, s[8:9]
	global_store_dwordx2 v[6:7], v[82:83], off
	v_lshl_add_u64 v[6:7], v[6:7], 0, s[10:11]
	v_mov_b32_e32 v86, 0
	v_dot2c_f32_bf16_e32 v86, v82, v82
	v_dot2c_f32_bf16_e32 v86, v83, v83
	v_add_u32_e32 v87, 0x20000, v2
	v_lshrrev_b32_e32 v87, 4, v87
	v_lshlrev_b32_e32 v87, 2, v87
	s_nop 1
	v_add_f32_dpp v86, v86, v86 quad_perm:[1,0,3,2] row_mask:0xf bank_mask:0xf
	s_nop 1
	v_add_f32_dpp v86, v86, v86 quad_perm:[2,3,0,1] row_mask:0xf bank_mask:0xf
	s_nop 1
	v_add_f32_dpp v86, v86, v86 row_half_mirror row_mask:0xf bank_mask:0xf
	s_nop 1
	v_add_f32_dpp v86, v86, v86 row_mirror row_mask:0xf bank_mask:0xf
	s_nop 1
	global_store_dword v87, v86, s[16:17]
	s_waitcnt vmcnt(11)
	global_store_dwordx4 v[4:5], v[56:59], off
	v_cvt_pk_bf16_f32 v80, v56, v57
	v_cvt_pk_bf16_f32 v81, v58, v59
	v_lshl_add_u64 v[4:5], v[4:5], 0, s[8:9]
	global_store_dwordx2 v[6:7], v[80:81], off
	v_lshl_add_u64 v[6:7], v[6:7], 0, s[10:11]
	v_mov_b32_e32 v84, 0
	v_dot2c_f32_bf16_e32 v84, v80, v80
	v_dot2c_f32_bf16_e32 v84, v81, v81
	v_add_u32_e32 v85, 0x40000, v2
	v_lshrrev_b32_e32 v85, 4, v85
	v_lshlrev_b32_e32 v85, 2, v85
	s_nop 1
	v_add_f32_dpp v84, v84, v84 quad_perm:[1,0,3,2] row_mask:0xf bank_mask:0xf
	s_nop 1
	v_add_f32_dpp v84, v84, v84 quad_perm:[2,3,0,1] row_mask:0xf bank_mask:0xf
	s_nop 1
	v_add_f32_dpp v84, v84, v84 row_half_mirror row_mask:0xf bank_mask:0xf
	s_nop 1
	v_add_f32_dpp v84, v84, v84 row_mirror row_mask:0xf bank_mask:0xf
	s_nop 1
	global_store_dword v85, v84, s[16:17]
	s_waitcnt vmcnt(13)
	global_store_dwordx4 v[4:5], v[60:63], off
	v_cvt_pk_bf16_f32 v82, v60, v61
	v_cvt_pk_bf16_f32 v83, v62, v63
	v_lshl_add_u64 v[4:5], v[4:5], 0, s[8:9]
	global_store_dwordx2 v[6:7], v[82:83], off
	v_lshl_add_u64 v[6:7], v[6:7], 0, s[10:11]
	v_mov_b32_e32 v86, 0
	v_dot2c_f32_bf16_e32 v86, v82, v82
	v_dot2c_f32_bf16_e32 v86, v83, v83
	v_add_u32_e32 v87, 0x60000, v2
	v_lshrrev_b32_e32 v87, 4, v87
	v_lshlrev_b32_e32 v87, 2, v87
	s_nop 1
	v_add_f32_dpp v86, v86, v86 quad_perm:[1,0,3,2] row_mask:0xf bank_mask:0xf
	s_nop 1
	v_add_f32_dpp v86, v86, v86 quad_perm:[2,3,0,1] row_mask:0xf bank_mask:0xf
	s_nop 1
	v_add_f32_dpp v86, v86, v86 row_half_mirror row_mask:0xf bank_mask:0xf
	s_nop 1
	v_add_f32_dpp v86, v86, v86 row_mirror row_mask:0xf bank_mask:0xf
	s_nop 1
	global_store_dword v87, v86, s[16:17]
	s_waitcnt vmcnt(15)
	global_store_dwordx4 v[4:5], v[64:67], off
	v_cvt_pk_bf16_f32 v80, v64, v65
	v_cvt_pk_bf16_f32 v81, v66, v67
	v_lshl_add_u64 v[4:5], v[4:5], 0, s[8:9]
	global_store_dwordx2 v[6:7], v[80:81], off
	v_lshl_add_u64 v[6:7], v[6:7], 0, s[10:11]
	v_mov_b32_e32 v84, 0
	v_dot2c_f32_bf16_e32 v84, v80, v80
	v_dot2c_f32_bf16_e32 v84, v81, v81
	v_add_u32_e32 v85, 0x80000, v2
	v_lshrrev_b32_e32 v85, 4, v85
	v_lshlrev_b32_e32 v85, 2, v85
	s_nop 1
	v_add_f32_dpp v84, v84, v84 quad_perm:[1,0,3,2] row_mask:0xf bank_mask:0xf
	s_nop 1
	v_add_f32_dpp v84, v84, v84 quad_perm:[2,3,0,1] row_mask:0xf bank_mask:0xf
	s_nop 1
	v_add_f32_dpp v84, v84, v84 row_half_mirror row_mask:0xf bank_mask:0xf
	s_nop 1
	v_add_f32_dpp v84, v84, v84 row_mirror row_mask:0xf bank_mask:0xf
	s_nop 1
	global_store_dword v85, v84, s[16:17]
	s_waitcnt vmcnt(17)
	global_store_dwordx4 v[4:5], v[68:71], off
	v_cvt_pk_bf16_f32 v82, v68, v69
	v_cvt_pk_bf16_f32 v83, v70, v71
	v_lshl_add_u64 v[4:5], v[4:5], 0, s[8:9]
	global_store_dwordx2 v[6:7], v[82:83], off
	v_lshl_add_u64 v[6:7], v[6:7], 0, s[10:11]
	v_mov_b32_e32 v86, 0
	v_dot2c_f32_bf16_e32 v86, v82, v82
	v_dot2c_f32_bf16_e32 v86, v83, v83
	v_add_u32_e32 v87, 0xa0000, v2
	v_lshrrev_b32_e32 v87, 4, v87
	v_lshlrev_b32_e32 v87, 2, v87
	s_nop 1
	v_add_f32_dpp v86, v86, v86 quad_perm:[1,0,3,2] row_mask:0xf bank_mask:0xf
	s_nop 1
	v_add_f32_dpp v86, v86, v86 quad_perm:[2,3,0,1] row_mask:0xf bank_mask:0xf
	s_nop 1
	v_add_f32_dpp v86, v86, v86 row_half_mirror row_mask:0xf bank_mask:0xf
	s_nop 1
	v_add_f32_dpp v86, v86, v86 row_mirror row_mask:0xf bank_mask:0xf
	s_nop 1
	global_store_dword v87, v86, s[16:17]
	s_waitcnt vmcnt(19)
	global_store_dwordx4 v[4:5], v[72:75], off
	v_cvt_pk_bf16_f32 v80, v72, v73
	v_cvt_pk_bf16_f32 v81, v74, v75
	v_lshl_add_u64 v[4:5], v[4:5], 0, s[8:9]
	global_store_dwordx2 v[6:7], v[80:81], off
	v_lshl_add_u64 v[6:7], v[6:7], 0, s[10:11]
	v_mov_b32_e32 v84, 0
	v_dot2c_f32_bf16_e32 v84, v80, v80
	v_dot2c_f32_bf16_e32 v84, v81, v81
	v_add_u32_e32 v85, 0xc0000, v2
	v_lshrrev_b32_e32 v85, 4, v85
	v_lshlrev_b32_e32 v85, 2, v85
	s_nop 1
	v_add_f32_dpp v84, v84, v84 quad_perm:[1,0,3,2] row_mask:0xf bank_mask:0xf
	s_nop 1
	v_add_f32_dpp v84, v84, v84 quad_perm:[2,3,0,1] row_mask:0xf bank_mask:0xf
	s_nop 1
	v_add_f32_dpp v84, v84, v84 row_half_mirror row_mask:0xf bank_mask:0xf
	s_nop 1
	v_add_f32_dpp v84, v84, v84 row_mirror row_mask:0xf bank_mask:0xf
	s_nop 1
	global_store_dword v85, v84, s[16:17]
	s_waitcnt vmcnt(21)
	global_store_dwordx4 v[4:5], v[76:79], off
	v_cvt_pk_bf16_f32 v82, v76, v77
	v_cvt_pk_bf16_f32 v83, v78, v79
	v_lshl_add_u64 v[4:5], v[4:5], 0, s[8:9]
	global_store_dwordx2 v[6:7], v[82:83], off
	v_lshl_add_u64 v[6:7], v[6:7], 0, s[10:11]
	v_mov_b32_e32 v86, 0
	v_dot2c_f32_bf16_e32 v86, v82, v82
	v_dot2c_f32_bf16_e32 v86, v83, v83
	v_add_u32_e32 v87, 0xe0000, v2
	v_lshrrev_b32_e32 v87, 4, v87
	v_lshlrev_b32_e32 v87, 2, v87
	s_nop 1
	v_add_f32_dpp v86, v86, v86 quad_perm:[1,0,3,2] row_mask:0xf bank_mask:0xf
	s_nop 1
	v_add_f32_dpp v86, v86, v86 quad_perm:[2,3,0,1] row_mask:0xf bank_mask:0xf
	s_nop 1
	v_add_f32_dpp v86, v86, v86 row_half_mirror row_mask:0xf bank_mask:0xf
	s_nop 1
	v_add_f32_dpp v86, v86, v86 row_mirror row_mask:0xf bank_mask:0xf
	s_nop 1
	global_store_dword v87, v86, s[16:17]
	v_add_u32_e32 v2, 0x100000, v2
	s_add_i32 s12, s12, 1
	s_cmp_lt_i32 s12, 4
	s_cbranch_scc1 .Linit_loop
; DI int opaque_tid() { int t = threadIdx.x; asm volatile("" : "+v"(t)); return t; }
; DI void init_h(const Params& p) {
;     ...
;   for (size_t i = (size_t)blockIdx.x * NT + opaque_tid(); i < n4; i += (size_t)gridDim.x * NT) {
;     const size_t e = i * 4;
;     const int row = (int)(e / D), col = (int)(e % D);
;     const int b = row / T, t = row % T;
;     f32x4 v = t < 16 ? *(const f32x4*)(p.meta + (size_t)t * D + col) : *(const f32x4*)(p.x + ((size_t)b * 2048 + (t - 16)) * D + col);
;     *(f32x4*)(h + e) = v;
;     *(u32x2*)(hb + e) = MK2(pack2(v[0], v[1]), pack2(v[2], v[3]));
;   }
	s_mov_b32 s6, 0x408000
	v_cmp_gt_u32_e32 vcc, s6, v2
	s_and_saveexec_b64 s[18:19], vcc
	s_cbranch_execz .Linit_tail_done
	v_mov_b32_e32 v22, v2
	v_lshrrev_b32_e32 v23, 8, v22
	v_and_b32_e32 v22, 0xff, v22
	v_mul_u32_u24_e32 v24, 0x3f81, v23
	v_lshrrev_b32_e32 v24, 25, v24
	v_mul_u32_u24_e32 v25, 0x810, v24
	v_sub_u32_e32 v25, v23, v25
	v_cmp_lt_u32_e32 vcc, 15, v25
	v_lshl_add_u32 v26, v24, 11, v25
	v_add_u32_e32 v26, -16, v26
	v_lshlrev_b32_e32 v22, 4, v22
	v_cndmask_b32_e32 v26, v25, v26, vcc
	v_cndmask_b32_e32 v28, v16, v18, vcc
	v_cndmask_b32_e32 v29, v17, v19, vcc
	v_lshl_or_b32 v20, v26, 12, v22
	v_lshl_add_u64 v[30:31], v[20:21], 0, v[28:29]
	global_load_dwordx4 v[48:51], v[30:31], off
	s_waitcnt vmcnt(0)
	global_store_dwordx4 v[4:5], v[48:51], off
	v_cvt_pk_bf16_f32 v80, v48, v49
	v_cvt_pk_bf16_f32 v81, v50, v51
	v_lshl_add_u64 v[4:5], v[4:5], 0, s[8:9]
	global_store_dwordx2 v[6:7], v[80:81], off
	v_lshl_add_u64 v[6:7], v[6:7], 0, s[10:11]
	v_mov_b32_e32 v84, 0
	v_dot2c_f32_bf16_e32 v84, v80, v80
	v_dot2c_f32_bf16_e32 v84, v81, v81
	v_mov_b32_e32 v85, v2
	v_lshrrev_b32_e32 v85, 4, v85
	v_lshlrev_b32_e32 v85, 2, v85
	s_nop 1
	v_add_f32_dpp v84, v84, v84 quad_perm:[1,0,3,2] row_mask:0xf bank_mask:0xf
	s_nop 1
	v_add_f32_dpp v84, v84, v84 quad_perm:[2,3,0,1] row_mask:0xf bank_mask:0xf
	s_nop 1
	v_add_f32_dpp v84, v84, v84 row_half_mirror row_mask:0xf bank_mask:0xf
	s_nop 1
	v_add_f32_dpp v84, v84, v84 row_mirror row_mask:0xf bank_mask:0xf
	s_nop 1
	global_store_dword v85, v84, s[16:17]
.Linit_tail_done:
	s_or_b64 exec, exec, s[18:19]
	s_branch .LBB0_12
.Linit_generic:
	v_ashrrev_i32_e32 v9, 31, v8
	v_readlane_b32 s2, v252, 0
	v_readlane_b32 s3, v252, 1
	s_lshl_b64 s[2:3], s[2:3], 9
	s_nop 0
	v_lshl_add_u64 v[2:3], s[2:3], 0, v[8:9]
	s_mov_b64 s[2:3], 0x408000
	v_cmp_gt_u64_e32 vcc, s[2:3], v[2:3]
	s_and_saveexec_b64 s[2:3], vcc
	s_cbranch_execz .LBB0_12
	v_readlane_b32 s14, v252, 0
	s_mov_b32 s13, 0
	s_mov_b32 s12, s26
	v_readlane_b32 s15, v252, 1
	s_lshl_b64 s[6:7], s[12:13], 9
	s_lshl_b64 s[8:9], s[14:15], 13
	s_add_u32 s8, s24, s8
	s_addc_u32 s9, s25, s9
	v_lshl_add_u64 v[4:5], v[8:9], 4, s[8:9]
	s_lshl_b64 s[8:9], s[12:13], 13
	s_lshl_b64 s[10:11], s[14:15], 12
	s_add_u32 s10, s24, s10
	s_addc_u32 s11, s25, s11
	v_lshl_add_u64 v[6:7], v[8:9], 3, s[10:11]
	s_mov_b64 s[10:11], 0x4080000
	s_lshl_b64 s[14:15], s[14:15], 11
	v_lshl_add_u64 v[6:7], v[6:7], 0, s[10:11]
	s_lshl_b64 s[10:11], s[12:13], 12
	v_lshl_add_u64 v[8:9], v[8:9], 2, s[14:15]
	s_lshl_b64 s[12:13], s[12:13], 11
	s_mov_b64 s[14:15], 0
	v_mov_b32_e32 v11, 0
	s_mov_b64 s[16:17], 0x407fff
	s_branch .LBB0_8

; DI float shx(float v, int mask, int lane) { return __int_as_float(__builtin_amdgcn_ds_bpermute((lane ^ mask) << 2, __float_as_int(v))); }
; DI void gemm_run(const GemmCfg c, char* smem, float* const g_h, u16* const g_hb, float* const g_out, const int final_out) {
;     ...
;   for (int slot = Lb; slot < ntiles; slot += G) {
;     const int sr = slot / srow, idx = slot - sr * srow;
;     const int tm = sr < 8 ? sr * 8 + (idx & 7) : 64;
;     const int tn = sr < 8 ? (idx >> 3) : idx;
;     const u16* Ag = c.A + (size_t)(tm * 256 + lrow) * c.lda + tn * c.a_koff_tn + lch * 8;
;     const u16* Bg = c.Bt + (size_t)(tn * 256 + lrow) * K + lch * 8;
;     const size_t astep = (size_t)64 * c.lda, bstep = (size_t)64 * K;
;     ...
;     if (c.use_rs) {
; #pragma unroll
;       for (int i = 0; i < 4; ++i) {
;         float s_ = ss[i];
;         s_ += shx(s_, 1, lane); s_ += shx(s_, 2, lane); s_ += shx(s_, 4, lane);
;         if (lch == 0) s_rowss[lrow + 64 * i] = s_;
;       }
.LBB0_110:
	s_abs_i32 s1, s48
	s_mul_hi_u32 s4, s1, s69
	s_mul_i32 s5, s4, s30
	s_ashr_i32 s0, s48, 31
	s_sub_i32 s1, s1, s5
	s_xor_b32 s0, s0, s63
	s_add_i32 s5, s4, 1
	s_sub_i32 s6, s1, s30
	s_cmp_ge_u32 s1, s30
	s_cselect_b32 s4, s5, s4
	s_cselect_b32 s1, s6, s1
	s_add_i32 s5, s4, 1
	s_cmp_ge_u32 s1, s30
	s_cselect_b32 s1, s5, s4
	s_xor_b32 s1, s1, s0
	s_sub_i32 s0, s1, s0
	s_mul_i32 s1, s0, s65
	s_sub_i32 s1, s48, s1
	s_lshl_b32 s4, s0, 3
	s_and_b32 s5, s48, 7
	s_or_b32 s4, s4, s5
	s_ashr_i32 s5, s1, 3
	s_cmp_lt_i32 s0, 8
	s_cselect_b32 s78, s4, 64
	s_waitcnt lgkmcnt(0)
	s_cselect_b32 s49, s5, s1
	v_lshrrev_b32_e32 v128, 3, v185
	v_and_b32_e32 v129, 7, v185
	v_xor_b32_e32 v129, v129, v128
	v_lshlrev_b32_e32 v129, 4, v129
	s_lshl_b32 s0, s62, 1
	v_mul_lo_u32 v130, v128, s0
	s_lshl_b32 s1, s62, 4
	v_add_u32_e32 v130, v130, v129
	v_add_u32_e32 v131, s1, v130
	v_add_u32_e32 v132, s1, v131
	v_add_u32_e32 v133, s1, v132
	s_lshl_b32 s0, s60, 1
	v_mul_lo_u32 v134, v128, s0
	s_lshl_b32 s1, s60, 4
	v_add_u32_e32 v134, v134, v129
	v_add_u32_e32 v135, s1, v134
	v_add_u32_e32 v136, s1, v135
	v_add_u32_e32 v137, s1, v136
	s_lshl_b32 s8, s75, 5
	s_add_i32 s8, s8, s86
	s_lshl_b32 s0, s78, 8
	s_add_i32 s0, s0, s8
	s_mul_i32 s0, s0, s62
	s_mul_i32 s1, s49, s2
	s_add_i32 s0, s0, s1
	s_lshl_b32 s0, s0, 1
	s_add_u32 s4, s54, s0
	s_addc_u32 s5, s55, 0
	v_readlane_b32 s6, v255, 5
	v_readlane_b32 s7, v255, 6
	s_lshl_b32 s0, s49, 8
	s_add_i32 s0, s0, s8
	s_mul_i32 s0, s0, s60
	s_lshl_b32 s0, s0, 1
	s_add_u32 s6, s6, s0
	s_addc_u32 s7, s7, 0
	s_lshl_b32 s8, s8, 7
	s_add_i32 s9, s75, 1
	s_and_b32 s9, s9, s88
	s_mov_b32 s1, 0
	s_cmp_eq_u32 s9, 0
	s_cbranch_scc1 .Lgemm_rsp_skip
	s_cmpk_lg_i32 s62, 0x400
	s_cbranch_scc1 .Lgemm_rsp_skip
	s_cmp_gt_u32 s78, 63
	s_cbranch_scc1 .Lgemm_rsp_skip
	v_readlane_b32 s0, v254, 38
	v_readlane_b32 s1, v254, 34
	s_nop 1
	s_add_i32 s1, s1, -1
	s_or_b32 s0, s0, s1
	s_mov_b32 s1, 0
	v_readlane_b32 s0, v255, 3
	v_readlane_b32 s1, v255, 4
	s_nop 1
	s_add_u32 s0, s0, 0x11f69000
	s_addc_u32 s1, s1, 0
	s_lshl_b32 s9, s78, 14
	s_add_u32 s0, s0, s9
	s_addc_u32 s1, s1, 0
	v_lshlrev_b32_e32 v221, 5, v210
	global_load_dwordx4 v[156:159], v221, s[0:1]
	global_load_dwordx2 v[208:209], v221, s[0:1] offset:16
	global_load_dwordx2 v[218:219], v221, s[0:1] offset:24
	s_mov_b32 s9, 0
	s_mov_b32 s1, 1
